# gate-up GEMM conv+SiLU epilogue: neighbour rows via DPP row rotates instead of ds_bpermute
# speedup vs baseline: 1.0136x; 1.0020x over previous
.LBB0_1003:
	v_mov_b32_dpp v181, v24 row_ror:1 row_mask:0xf bank_mask:0xf
	v_mov_b32_dpp v183, v25 row_ror:1 row_mask:0xf bank_mask:0xf
	v_mov_b32_dpp v185, v26 row_ror:1 row_mask:0xf bank_mask:0xf
	v_mov_b32_dpp v182, v24 row_ror:15 row_mask:0xf bank_mask:0xf
	v_mov_b32_dpp v190, v124 row_ror:15 row_mask:0xf bank_mask:0xf
	v_mov_b32_dpp v184, v25 row_ror:15 row_mask:0xf bank_mask:0xf
	v_mov_b32_dpp v186, v26 row_ror:15 row_mask:0xf bank_mask:0xf
	v_mov_b32_dpp v192, v125 row_ror:15 row_mask:0xf bank_mask:0xf
	v_mov_b32_dpp v194, v126 row_ror:15 row_mask:0xf bank_mask:0xf
	s_waitcnt lgkmcnt(0)
	v_cndmask_b32_e64 v128, v181, v128, s[14:15]
	s_waitcnt lgkmcnt(0)
	v_cndmask_b32_e64 v129, v183, v129, s[14:15]
	s_waitcnt lgkmcnt(0)
	v_cndmask_b32_e64 v130, v185, v130, s[14:15]
	v_mul_f32_e32 v128, v146, v128
	s_waitcnt lgkmcnt(0)
	v_cndmask_b32_e64 v182, v182, v190, s[16:17]
	v_mul_f32_e32 v130, v148, v130
	v_mul_f32_e32 v129, v147, v129
	v_fmac_f32_e32 v128, v24, v140
	s_waitcnt lgkmcnt(0)
	v_cndmask_b32_e64 v186, v186, v194, s[16:17]
	v_fmac_f32_e32 v130, v26, v142
	v_cndmask_b32_e64 v184, v184, v192, s[16:17]
	v_fmac_f32_e32 v129, v25, v141
	v_fmac_f32_e32 v128, v132, v182
	v_fmac_f32_e32 v130, v134, v186
	v_fmac_f32_e32 v129, v133, v184
	v_add_f32_e32 v128, v136, v128
	v_add_f32_e32 v130, v138, v130
	v_add_f32_e32 v129, v137, v129
	v_mul_f32_e32 v182, 0xbfb8aa3b, v128
	v_mul_f32_e32 v186, 0xbfb8aa3b, v130
	v_mul_f32_e32 v184, 0xbfb8aa3b, v129
	v_exp_f32_e32 v182, v182
	v_exp_f32_e32 v186, v186
	v_exp_f32_e32 v184, v184
	v_mov_b32_dpp v187, v27 row_ror:1 row_mask:0xf bank_mask:0xf
	v_add_f32_e32 v182, 1.0, v182
	v_add_f32_e32 v186, 1.0, v186
	v_add_f32_e32 v184, 1.0, v184
	v_rcp_f32_e32 v182, v182
	v_mov_b32_dpp v189, v124 row_ror:1 row_mask:0xf bank_mask:0xf
	v_mov_b32_dpp v195, v127 row_ror:1 row_mask:0xf bank_mask:0xf
	v_rcp_f32_e32 v186, v186
	v_rcp_f32_e32 v184, v184
	v_mov_b32_dpp v196, v127 row_ror:15 row_mask:0xf bank_mask:0xf
	v_mov_b32_dpp v204, v119 row_ror:15 row_mask:0xf bank_mask:0xf
	v_mul_f32_e32 v128, v128, v182
	v_mul_f32_e32 v130, v130, v186
	v_mul_f32_e32 v129, v129, v184
	v_mul_f32_e32 v128, v28, v128
	v_mul_f32_e32 v186, v30, v130
	v_mul_f32_e32 v129, v29, v129
	v_cvt_pk_bf16_f32 v130, v128, v129
	s_waitcnt lgkmcnt(0)
	v_cndmask_b32_e64 v128, v189, v181, s[14:15]
	s_waitcnt lgkmcnt(0)
	v_cndmask_b32_e64 v181, v195, v187, s[14:15]
	v_mov_b32_dpp v193, v126 row_ror:1 row_mask:0xf bank_mask:0xf
	v_mul_f32_e32 v181, v149, v181
	s_waitcnt lgkmcnt(0)
	v_cndmask_b32_e64 v182, v196, v204, s[16:17]
	v_fmac_f32_e32 v181, v127, v143
	v_mov_b32_dpp v202, v118 row_ror:15 row_mask:0xf bank_mask:0xf
	v_fmac_f32_e32 v181, v135, v182
	v_add_f32_e32 v127, v139, v181
	v_mul_f32_e32 v181, 0xbfb8aa3b, v127
	v_mov_b32_dpp v191, v125 row_ror:1 row_mask:0xf bank_mask:0xf
	v_exp_f32_e32 v181, v181
	s_waitcnt lgkmcnt(0)
	v_cndmask_b32_e64 v182, v193, v185, s[14:15]
	v_mov_b32_dpp v188, v27 row_ror:15 row_mask:0xf bank_mask:0xf
	v_mul_f32_e32 v182, v148, v182
	v_mov_b32_dpp v198, v116 row_ror:15 row_mask:0xf bank_mask:0xf
	v_mov_b32_dpp v200, v117 row_ror:15 row_mask:0xf bank_mask:0xf
	s_waitcnt lgkmcnt(0)
	v_cndmask_b32_e64 v184, v194, v202, s[16:17]
	v_fmac_f32_e32 v182, v126, v142
	v_fmac_f32_e32 v182, v134, v184
	v_cndmask_b32_e64 v131, v187, v131, s[14:15]
	v_add_f32_e32 v181, 1.0, v181
	v_add_f32_e32 v126, v138, v182
	v_mul_f32_e32 v131, v149, v131
	s_waitcnt lgkmcnt(0)
	v_cndmask_b32_e64 v129, v191, v183, s[14:15]
	v_rcp_f32_e32 v181, v181
	v_mul_f32_e32 v182, 0xbfb8aa3b, v126
	s_waitcnt lgkmcnt(0)
	v_cndmask_b32_e64 v188, v188, v196, s[16:17]
	v_fmac_f32_e32 v131, v27, v143
	v_exp_f32_e32 v182, v182
	v_mul_f32_e32 v129, v147, v129
	v_mul_f32_e32 v128, v146, v128
	v_fmac_f32_e32 v131, v135, v188
	s_waitcnt lgkmcnt(0)
	v_cndmask_b32_e64 v183, v190, v198, s[16:17]
	s_waitcnt lgkmcnt(0)
	v_cndmask_b32_e64 v184, v192, v200, s[16:17]
	v_fmac_f32_e32 v129, v125, v141
	v_fmac_f32_e32 v128, v124, v140
	v_add_f32_e32 v131, v139, v131
	v_fmac_f32_e32 v129, v133, v184
	v_fmac_f32_e32 v128, v132, v183
	v_mul_f32_e32 v188, 0xbfb8aa3b, v131
	v_mul_f32_e32 v127, v127, v181
	v_add_f32_e32 v125, v137, v129
	v_add_f32_e32 v124, v136, v128
	v_exp_f32_e32 v188, v188
	v_mul_f32_e32 v123, v123, v127
	v_add_f32_e32 v127, 1.0, v182
	v_mul_f32_e32 v129, 0xbfb8aa3b, v125
	v_mul_f32_e32 v128, 0xbfb8aa3b, v124
	v_rcp_f32_e32 v127, v127
	v_exp_f32_e32 v129, v129
	v_exp_f32_e32 v128, v128
	v_add_f32_e32 v188, 1.0, v188
	v_rcp_f32_e32 v188, v188
	v_mul_f32_e32 v126, v126, v127
	v_add_f32_e32 v127, 1.0, v129
	v_add_f32_e32 v128, 1.0, v128
	v_mov_b32_dpp v203, v119 row_ror:1 row_mask:0xf bank_mask:0xf
	v_rcp_f32_e32 v127, v127
	v_rcp_f32_e32 v128, v128
	v_mov_b32_dpp v212, v107 row_ror:15 row_mask:0xf bank_mask:0xf
	v_mul_f32_e32 v131, v131, v188
	v_mul_f32_e32 v131, v31, v131
	v_mul_f32_e32 v122, v122, v126
	v_mul_f32_e32 v125, v125, v127
	v_mul_f32_e32 v124, v124, v128
	v_cvt_pk_bf16_f32 v131, v186, v131
	v_mul_f32_e32 v121, v121, v125
	v_mul_f32_e32 v120, v120, v124
	v_cvt_pk_bf16_f32 v128, v120, v121
	v_cvt_pk_bf16_f32 v129, v122, v123
	s_waitcnt lgkmcnt(0)
	v_cndmask_b32_e64 v122, v203, v195, s[14:15]
	v_mov_b32_dpp v201, v118 row_ror:1 row_mask:0xf bank_mask:0xf
	v_mul_f32_e32 v122, v149, v122
	s_waitcnt lgkmcnt(0)
	v_cndmask_b32_e64 v123, v204, v212, s[16:17]
	v_fmac_f32_e32 v122, v119, v143
	v_mov_b32_dpp v210, v106 row_ror:15 row_mask:0xf bank_mask:0xf
	v_fmac_f32_e32 v122, v135, v123
	v_mov_b32_dpp v197, v116 row_ror:1 row_mask:0xf bank_mask:0xf
	v_add_f32_e32 v119, v139, v122
	v_mul_f32_e32 v122, 0xbfb8aa3b, v119
	v_mov_b32_dpp v199, v117 row_ror:1 row_mask:0xf bank_mask:0xf
	v_mov_b32_dpp v206, v104 row_ror:15 row_mask:0xf bank_mask:0xf
	v_exp_f32_e32 v122, v122
	s_waitcnt lgkmcnt(0)
	v_cndmask_b32_e64 v123, v201, v193, s[14:15]
	v_mul_f32_e32 v123, v148, v123
	v_mov_b32_dpp v208, v105 row_ror:15 row_mask:0xf bank_mask:0xf
	s_waitcnt lgkmcnt(0)
	v_cndmask_b32_e64 v125, v202, v210, s[16:17]
	v_fmac_f32_e32 v123, v118, v142
	s_waitcnt lgkmcnt(0)
	v_cndmask_b32_e64 v120, v197, v189, s[14:15]
	v_fmac_f32_e32 v123, v134, v125
	v_add_f32_e32 v122, 1.0, v122
	v_add_f32_e32 v118, v138, v123
	v_mul_f32_e32 v120, v146, v120
	s_waitcnt lgkmcnt(0)
	v_cndmask_b32_e64 v121, v199, v191, s[14:15]
	s_waitcnt lgkmcnt(0)
	v_cndmask_b32_e64 v124, v198, v206, s[16:17]
	v_rcp_f32_e32 v122, v122
	v_mul_f32_e32 v123, 0xbfb8aa3b, v118
	v_fmac_f32_e32 v120, v116, v140
	v_exp_f32_e32 v123, v123
	v_mul_f32_e32 v121, v147, v121
	v_fmac_f32_e32 v120, v132, v124
	s_waitcnt lgkmcnt(0)
	v_cndmask_b32_e64 v125, v200, v208, s[16:17]
	v_fmac_f32_e32 v121, v117, v141
	v_add_f32_e32 v116, v136, v120
	v_fmac_f32_e32 v121, v133, v125
	v_mul_f32_e32 v120, 0xbfb8aa3b, v116
	v_mul_f32_e32 v119, v119, v122
	v_add_f32_e32 v117, v137, v121
	v_exp_f32_e32 v120, v120
	v_mul_f32_e32 v115, v115, v119
	v_add_f32_e32 v119, 1.0, v123
	v_mul_f32_e32 v121, 0xbfb8aa3b, v117
	v_rcp_f32_e32 v119, v119
	v_exp_f32_e32 v121, v121
	v_add_f32_e32 v120, 1.0, v120
	v_mov_b32_dpp v211, v107 row_ror:1 row_mask:0xf bank_mask:0xf
	v_rcp_f32_e32 v120, v120
	v_mul_f32_e32 v118, v118, v119
	v_add_f32_e32 v119, 1.0, v121
	v_rcp_f32_e32 v119, v119
	v_mul_f32_e32 v116, v116, v120
	v_mul_f32_e32 v112, v112, v116
	s_waitcnt lgkmcnt(0)
	v_cndmask_b32_e64 v116, v211, v203, s[14:15]
	v_mov_b32_dpp v209, v106 row_ror:1 row_mask:0xf bank_mask:0xf
	v_mul_f32_e32 v117, v117, v119
	v_mul_f32_e32 v116, v149, v116
	v_mul_f32_e32 v113, v113, v117
	v_cndmask_b32_e64 v117, v212, v153, s[16:17]
	v_fmac_f32_e32 v116, v107, v143
	v_fmac_f32_e32 v116, v135, v117
	v_add_f32_e32 v107, v139, v116
	v_mul_f32_e32 v116, 0xbfb8aa3b, v107
	v_mov_b32_dpp v205, v104 row_ror:1 row_mask:0xf bank_mask:0xf
	v_mov_b32_dpp v207, v105 row_ror:1 row_mask:0xf bank_mask:0xf
	v_exp_f32_e32 v116, v116
	s_waitcnt lgkmcnt(0)
	v_cndmask_b32_e64 v117, v209, v201, s[14:15]
	v_mul_f32_e32 v117, v148, v117
	v_cndmask_b32_e64 v119, v210, v152, s[16:17]
	v_fmac_f32_e32 v117, v106, v142
	v_fmac_f32_e32 v117, v134, v119
	v_mul_f32_e32 v114, v114, v118
	v_add_f32_e32 v116, 1.0, v116
	v_add_f32_e32 v106, v138, v117
	v_cvt_pk_bf16_f32 v112, v112, v113
	v_cvt_pk_bf16_f32 v113, v114, v115
	s_waitcnt lgkmcnt(0)
	v_cndmask_b32_e64 v114, v205, v197, s[14:15]
	s_waitcnt lgkmcnt(0)
	v_cndmask_b32_e64 v115, v207, v199, s[14:15]
	v_rcp_f32_e32 v116, v116
	v_mul_f32_e32 v117, 0xbfb8aa3b, v106
	v_exp_f32_e32 v117, v117
	v_mul_f32_e32 v115, v147, v115
	v_mul_f32_e32 v114, v146, v114
	v_cndmask_b32_e64 v118, v206, v150, s[16:17]
	v_cndmask_b32_e64 v119, v208, v151, s[16:17]
	v_fmac_f32_e32 v115, v105, v141
	v_fmac_f32_e32 v114, v104, v140
	v_fmac_f32_e32 v115, v133, v119
	v_fmac_f32_e32 v114, v132, v118
	v_mul_f32_e32 v107, v107, v116
	v_add_f32_e32 v105, v137, v115
	v_add_f32_e32 v104, v136, v114
	v_mul_f32_e32 v107, v111, v107
	v_add_f32_e32 v111, 1.0, v117
	v_mul_f32_e32 v115, 0xbfb8aa3b, v105
	v_mul_f32_e32 v114, 0xbfb8aa3b, v104
	v_rcp_f32_e32 v111, v111
	v_exp_f32_e32 v115, v115
	v_exp_f32_e32 v114, v114
	v_mov_b32_e32 v134, 0
	v_mul_f32_e32 v106, v106, v111
	v_add_f32_e32 v111, 1.0, v115
	v_add_f32_e32 v114, 1.0, v114
	v_rcp_f32_e32 v111, v111
	v_rcp_f32_e32 v114, v114
	v_mul_f32_e32 v106, v110, v106
	s_andn2_b64 vcc, exec, s[10:11]
	v_mul_f32_e32 v105, v105, v111
	v_mul_f32_e32 v104, v104, v114
	v_mul_f32_e32 v105, v109, v105
	v_mul_f32_e32 v104, v108, v104
	v_cvt_pk_bf16_f32 v104, v104, v105
	v_cvt_pk_bf16_f32 v105, v106, v107
	ds_read_b128 v[106:109], v174 offset:16
	ds_read_b128 v[120:123], v174 offset:528
	ds_read_b128 v[124:127], v174 offset:1040
	ds_read_b128 v[116:119], v174 offset:1552
	v_mov_b32_e32 v138, 0
	v_mov_b32_e32 v139, 0
	v_mov_b32_e32 v140, 0
	v_mov_b32_e32 v141, 0
	s_cbranch_vccnz .LBB0_1005
	ds_read_b128 v[138:141], v179

.LBB0_1007:
	v_mov_b32_dpp v114, v15 row_ror:15 row_mask:0xf bank_mask:0xf
	v_mov_b32_dpp v186, v103 row_ror:15 row_mask:0xf bank_mask:0xf
	v_mov_b32_dpp v143, v12 row_ror:1 row_mask:0xf bank_mask:0xf
	v_mov_b32_dpp v151, v15 row_ror:1 row_mask:0xf bank_mask:0xf
	v_mov_b32_e32 v132, v15
	s_waitcnt lgkmcnt(0)
	v_mov_b32_e32 v133, v127
	s_waitcnt lgkmcnt(0)
	v_cndmask_b32_e64 v115, v114, v186, s[16:17]
	v_mov_b32_e32 v114, v123
	s_waitcnt lgkmcnt(0)
	v_cndmask_b32_e64 v203, v143, v138, s[14:15]
	s_waitcnt lgkmcnt(0)
	v_cndmask_b32_e64 v138, v151, v141, s[14:15]
	v_pk_mul_f32 v[114:115], v[132:133], v[114:115]
	v_mov_b32_dpp v147, v13 row_ror:1 row_mask:0xf bank_mask:0xf
	v_fma_f32 v114, v109, v138, v114
	v_add_f32_e32 v114, v114, v115
	v_add_f32_e32 v114, v119, v114
	v_mul_f32_e32 v115, 0xbfb8aa3b, v114
	v_mov_b32_dpp v150, v14 row_ror:15 row_mask:0xf bank_mask:0xf
	v_mov_b32_dpp v184, v102 row_ror:15 row_mask:0xf bank_mask:0xf
	v_exp_f32_e32 v132, v115
	v_mov_b32_dpp v149, v14 row_ror:1 row_mask:0xf bank_mask:0xf
	s_waitcnt lgkmcnt(0)
	v_cndmask_b32_e64 v204, v147, v139, s[14:15]
	v_mov_b32_e32 v138, v14
	v_add_f32_e32 v132, 1.0, v132
	s_waitcnt lgkmcnt(0)
	v_cndmask_b32_e64 v133, v150, v184, s[16:17]
	v_rcp_f32_e32 v141, v132
	v_mov_b32_e32 v139, v126
	v_mov_b32_e32 v132, v122
	s_waitcnt lgkmcnt(0)
	v_cndmask_b32_e64 v140, v149, v140, s[14:15]
	v_pk_mul_f32 v[132:133], v[138:139], v[132:133]
	v_mov_b32_dpp v146, v12 row_ror:15 row_mask:0xf bank_mask:0xf
	v_fma_f32 v132, v108, v140, v132
	v_add_f32_e32 v132, v132, v133
	v_add_f32_e32 v140, v118, v132
	v_mul_f32_e32 v132, 0xbfb8aa3b, v140
	v_mov_b32_dpp v148, v13 row_ror:15 row_mask:0xf bank_mask:0xf
	v_mov_b32_dpp v153, v100 row_ror:15 row_mask:0xf bank_mask:0xf
	v_mov_b32_dpp v182, v101 row_ror:15 row_mask:0xf bank_mask:0xf
	v_exp_f32_e32 v132, v132
	v_mul_f32_e32 v114, v114, v141
	v_mul_f32_e32 v141, v23, v114
	s_waitcnt lgkmcnt(0)
	v_cndmask_b32_e64 v133, v146, v153, s[16:17]
	v_add_f32_e32 v114, 1.0, v132
	s_waitcnt lgkmcnt(0)
	v_cndmask_b32_e64 v115, v148, v182, s[16:17]
	v_rcp_f32_e32 v146, v114
	v_mov_b32_e32 v138, v13
	v_mov_b32_e32 v139, v125
	v_mov_b32_e32 v114, v121
	v_pk_mul_f32 v[114:115], v[138:139], v[114:115]
	v_mov_b32_e32 v132, v120
	v_fma_f32 v114, v107, v204, v114
	v_add_f32_e32 v114, v114, v115
	v_add_f32_e32 v138, v117, v114
	v_mul_f32_e32 v114, 0xbfb8aa3b, v138
	v_exp_f32_e32 v139, v114
	v_mov_b32_e32 v114, v12
	v_mov_b32_e32 v115, v124
	v_pk_mul_f32 v[114:115], v[114:115], v[132:133]
	v_add_f32_e32 v133, 1.0, v139
	v_fma_f32 v114, v106, v203, v114
	v_add_f32_e32 v114, v114, v115
	v_add_f32_e32 v114, v116, v114
	v_mul_f32_e32 v115, 0xbfb8aa3b, v114
	v_exp_f32_e32 v115, v115
	v_rcp_f32_e32 v133, v133
	v_mul_f32_e32 v132, v140, v146
	v_mov_b32_dpp v194, v95 row_ror:15 row_mask:0xf bank_mask:0xf
	v_add_f32_e32 v115, 1.0, v115
	v_rcp_f32_e32 v115, v115
	v_mul_f32_e32 v139, v22, v132
	v_mul_f32_e32 v132, v138, v133
	v_or_b32_e32 v110, s22, v167
	v_mov_b32_dpp v185, v103 row_ror:1 row_mask:0xf bank_mask:0xf
	v_mul_f32_e32 v132, v21, v132
	v_mul_f32_e32 v114, v114, v115
	v_lshl_add_u32 v142, s24, 8, v165
	v_ashrrev_i32_e32 v111, 31, v110
	v_mul_f32_e32 v114, v20, v114
	v_cvt_pk_bf16_f32 v132, v114, v132
	v_cvt_pk_bf16_f32 v133, v139, v141
	v_mov_b64_e32 v[140:141], s[28:29]
	s_movk_i32 s2, 0x2c00
	v_mad_i64_i32 v[114:115], s[20:21], v142, s2, v[140:141]
	v_lshlrev_b64 v[138:139], 1, v[110:111]
	v_lshl_add_u64 v[114:115], v[114:115], 0, v[138:139]
	global_store_dwordx4 v[114:115], v[130:133], off
	s_waitcnt lgkmcnt(0)
	v_cndmask_b32_e64 v114, v186, v194, s[16:17]
	v_mov_b32_e32 v115, v123
	v_mov_b32_e32 v130, v127
	v_mov_b32_e32 v131, v103
	s_waitcnt lgkmcnt(0)
	v_cndmask_b32_e64 v132, v185, v151, s[14:15]
	v_pk_mul_f32 v[114:115], v[130:131], v[114:115]
	v_mov_b32_dpp v192, v94 row_ror:15 row_mask:0xf bank_mask:0xf
	v_fma_f32 v103, v109, v132, v115
	v_add_f32_e32 v103, v114, v103
	v_add_f32_e32 v115, v119, v103
	v_mul_f32_e32 v103, 0xbfb8aa3b, v115
	v_mov_b32_dpp v181, v101 row_ror:1 row_mask:0xf bank_mask:0xf
	v_mov_b32_dpp v183, v102 row_ror:1 row_mask:0xf bank_mask:0xf
	v_exp_f32_e32 v103, v103
	s_waitcnt lgkmcnt(0)
	v_cndmask_b32_e64 v130, v184, v192, s[16:17]
	v_mov_b32_e32 v132, v126
	v_mov_b32_e32 v133, v102
	v_add_f32_e32 v103, 1.0, v103
	v_mov_b32_e32 v131, v122
	s_waitcnt lgkmcnt(0)
	v_cndmask_b32_e64 v146, v181, v147, s[14:15]
	s_waitcnt lgkmcnt(0)
	v_cndmask_b32_e64 v147, v183, v149, s[14:15]
	v_rcp_f32_e32 v148, v103
	v_pk_mul_f32 v[102:103], v[132:133], v[130:131]
	v_mov_b32_dpp v190, v93 row_ror:15 row_mask:0xf bank_mask:0xf
	v_fma_f32 v103, v108, v147, v103
	v_add_f32_e32 v102, v102, v103
	v_add_f32_e32 v132, v118, v102
	v_mul_f32_e32 v102, 0xbfb8aa3b, v132
	v_exp_f32_e32 v103, v102
	v_mov_b32_dpp v188, v92 row_ror:15 row_mask:0xf bank_mask:0xf
	s_waitcnt lgkmcnt(0)
	v_cndmask_b32_e64 v102, v182, v190, s[16:17]
	v_mov_b32_e32 v130, v125
	v_add_f32_e32 v103, 1.0, v103
	v_rcp_f32_e32 v133, v103
	v_mov_b32_e32 v131, v101
	v_mov_b32_e32 v103, v121
	v_mov_b32_dpp v152, v100 row_ror:1 row_mask:0xf bank_mask:0xf
	v_pk_mul_f32 v[102:103], v[130:131], v[102:103]
	v_mul_f32_e32 v115, v115, v148
	v_fma_f32 v101, v107, v146, v103
	v_add_f32_e32 v101, v102, v101
	v_add_f32_e32 v130, v117, v101
	s_waitcnt lgkmcnt(0)
	v_cndmask_b32_e64 v114, v153, v188, s[16:17]
	v_mul_f32_e32 v99, v99, v115
	v_mul_f32_e32 v101, 0xbfb8aa3b, v130
	v_mov_b32_e32 v102, v124
	v_mov_b32_e32 v103, v100
	v_mov_b32_e32 v115, v120
	s_waitcnt lgkmcnt(0)
	v_cndmask_b32_e64 v143, v152, v143, s[14:15]
	v_exp_f32_e32 v131, v101
	v_pk_mul_f32 v[100:101], v[102:103], v[114:115]
	v_mov_b32_dpp v202, v83 row_ror:15 row_mask:0xf bank_mask:0xf
	v_fma_f32 v101, v106, v143, v101
	v_add_f32_e32 v100, v100, v101
	v_add_f32_e32 v100, v116, v100
	v_mul_f32_e32 v101, 0xbfb8aa3b, v100
	v_exp_f32_e32 v101, v101
	v_add_f32_e32 v103, 1.0, v131
	v_rcp_f32_e32 v103, v103
	v_mul_f32_e32 v102, v132, v133
	v_add_f32_e32 v101, 1.0, v101
	v_rcp_f32_e32 v101, v101
	v_mov_b32_dpp v193, v95 row_ror:1 row_mask:0xf bank_mask:0xf
	v_mul_f32_e32 v98, v98, v102
	v_mul_f32_e32 v102, v130, v103
	v_mul_f32_e32 v100, v100, v101
	v_mul_f32_e32 v96, v96, v100
	v_mul_f32_e32 v97, v97, v102
	v_cvt_pk_bf16_f32 v130, v96, v97
	v_or_b32_e32 v96, 16, v142
	v_mad_i64_i32 v[96:97], s[20:21], v96, s2, v[140:141]
	v_lshl_add_u64 v[96:97], v[96:97], 0, v[138:139]
	v_cvt_pk_bf16_f32 v131, v98, v99
	global_store_dwordx4 v[96:97], v[128:131], off
	s_waitcnt lgkmcnt(0)
	v_cndmask_b32_e64 v96, v194, v202, s[16:17]
	v_mov_b32_e32 v98, v127
	v_mov_b32_e32 v99, v95
	v_mov_b32_e32 v97, v123
	s_waitcnt lgkmcnt(0)
	v_cndmask_b32_e64 v100, v193, v185, s[14:15]
	v_pk_mul_f32 v[96:97], v[98:99], v[96:97]
	v_mov_b32_dpp v200, v82 row_ror:15 row_mask:0xf bank_mask:0xf
	v_fma_f32 v95, v109, v100, v97
	v_add_f32_e32 v95, v96, v95
	v_add_f32_e32 v97, v119, v95
	v_mul_f32_e32 v95, 0xbfb8aa3b, v97
	v_mov_b32_dpp v191, v94 row_ror:1 row_mask:0xf bank_mask:0xf
	v_exp_f32_e32 v95, v95
	s_waitcnt lgkmcnt(0)
	v_cndmask_b32_e64 v98, v192, v200, s[16:17]
	v_mov_b32_e32 v100, v126
	v_mov_b32_e32 v101, v94
	v_add_f32_e32 v95, 1.0, v95
	v_mov_b32_e32 v99, v122
	s_waitcnt lgkmcnt(0)
	v_cndmask_b32_e64 v114, v191, v183, s[14:15]
	v_rcp_f32_e32 v115, v95
	v_pk_mul_f32 v[94:95], v[100:101], v[98:99]
	v_mov_b32_dpp v198, v81 row_ror:15 row_mask:0xf bank_mask:0xf
	v_fma_f32 v95, v108, v114, v95
	v_add_f32_e32 v94, v94, v95
	v_add_f32_e32 v100, v118, v94
	v_mul_f32_e32 v94, 0xbfb8aa3b, v100
	v_exp_f32_e32 v95, v94
	v_mov_b32_dpp v189, v93 row_ror:1 row_mask:0xf bank_mask:0xf
	v_mov_b32_dpp v196, v80 row_ror:15 row_mask:0xf bank_mask:0xf
	s_waitcnt lgkmcnt(0)
	v_cndmask_b32_e64 v94, v190, v198, s[16:17]
	v_add_f32_e32 v95, 1.0, v95
	v_rcp_f32_e32 v101, v95
	v_mov_b32_e32 v98, v125
	v_mov_b32_e32 v99, v93
	v_mov_b32_e32 v95, v121
	v_mov_b32_dpp v187, v92 row_ror:1 row_mask:0xf bank_mask:0xf
	s_waitcnt lgkmcnt(0)
	v_cndmask_b32_e64 v103, v189, v181, s[14:15]
	v_pk_mul_f32 v[94:95], v[98:99], v[94:95]
	v_mul_f32_e32 v97, v97, v115
	v_fma_f32 v93, v107, v103, v95
	v_add_f32_e32 v93, v94, v93
	v_add_f32_e32 v98, v117, v93
	s_waitcnt lgkmcnt(0)
	v_cndmask_b32_e64 v96, v188, v196, s[16:17]
	v_mul_f32_e32 v91, v91, v97
	v_mul_f32_e32 v93, 0xbfb8aa3b, v98
	v_mov_b32_e32 v94, v124
	v_mov_b32_e32 v95, v92
	v_mov_b32_e32 v97, v120
	s_waitcnt lgkmcnt(0)
	v_cndmask_b32_e64 v102, v187, v152, s[14:15]
	v_exp_f32_e32 v99, v93
	v_pk_mul_f32 v[92:93], v[94:95], v[96:97]
	v_mul_f32_e32 v94, v100, v101
	v_fma_f32 v93, v106, v102, v93
	v_add_f32_e32 v92, v92, v93
	v_add_f32_e32 v92, v116, v92
	v_mul_f32_e32 v93, 0xbfb8aa3b, v92
	v_exp_f32_e32 v93, v93
	v_add_f32_e32 v95, 1.0, v99
	v_rcp_f32_e32 v95, v95
	v_mov_b32_dpp v201, v83 row_ror:1 row_mask:0xf bank_mask:0xf
	v_add_f32_e32 v93, 1.0, v93
	v_rcp_f32_e32 v93, v93
	v_mul_f32_e32 v90, v90, v94
	v_mul_f32_e32 v94, v98, v95
	v_mul_f32_e32 v89, v89, v94
	v_mul_f32_e32 v92, v92, v93
	v_mul_f32_e32 v88, v88, v92
	v_cvt_pk_bf16_f32 v114, v88, v89
	v_or_b32_e32 v88, 32, v142
	v_mad_i64_i32 v[88:89], s[20:21], v88, s2, v[140:141]
	v_lshl_add_u64 v[88:89], v[88:89], 0, v[138:139]
	v_cvt_pk_bf16_f32 v115, v90, v91
	global_store_dwordx4 v[88:89], v[112:115], off
	v_cndmask_b32_e64 v88, v202, v137, s[16:17]
	v_mov_b32_e32 v90, v127
	v_mov_b32_e32 v91, v83
	v_mov_b32_e32 v89, v123
	s_waitcnt lgkmcnt(0)
	v_cndmask_b32_e64 v94, v201, v193, s[14:15]
	v_pk_mul_f32 v[88:89], v[90:91], v[88:89]
	v_mov_b32_dpp v199, v82 row_ror:1 row_mask:0xf bank_mask:0xf
	v_fma_f32 v83, v109, v94, v89
	v_add_f32_e32 v83, v88, v83
	v_add_f32_e32 v89, v119, v83
	v_mul_f32_e32 v83, 0xbfb8aa3b, v89
	v_exp_f32_e32 v83, v83
	v_cndmask_b32_e64 v90, v200, v136, s[16:17]
	v_mov_b32_e32 v127, v82
	v_mov_b32_e32 v91, v122
	v_add_f32_e32 v83, 1.0, v83
	s_waitcnt lgkmcnt(0)
	v_cndmask_b32_e64 v94, v199, v191, s[14:15]
	v_rcp_f32_e32 v95, v83
	v_pk_mul_f32 v[82:83], v[126:127], v[90:91]
	v_mov_b32_dpp v197, v81 row_ror:1 row_mask:0xf bank_mask:0xf
	v_fma_f32 v83, v108, v94, v83
	v_add_f32_e32 v82, v82, v83
	v_add_f32_e32 v94, v118, v82
	v_mul_f32_e32 v82, 0xbfb8aa3b, v94
	v_mul_f32_e32 v89, v89, v95
	v_cndmask_b32_e64 v88, v198, v135, s[16:17]
	v_exp_f32_e32 v83, v82
	v_mul_f32_e32 v87, v87, v89
	v_mov_b32_e32 v90, v125
	v_mov_b32_e32 v91, v81
	v_mov_b32_e32 v89, v121
	v_mov_b32_dpp v195, v80 row_ror:1 row_mask:0xf bank_mask:0xf
	s_waitcnt lgkmcnt(0)
	v_cndmask_b32_e64 v93, v197, v189, s[14:15]
	v_pk_mul_f32 v[88:89], v[90:91], v[88:89]
	v_add_f32_e32 v83, 1.0, v83
	v_fma_f32 v81, v107, v93, v89
	v_add_f32_e32 v81, v88, v81
	v_add_f32_e32 v88, v117, v81
	v_cndmask_b32_e64 v82, v196, v134, s[16:17]
	v_rcp_f32_e32 v95, v83
	v_mul_f32_e32 v81, 0xbfb8aa3b, v88
	v_mov_b32_e32 v125, v80
	v_mov_b32_e32 v83, v120
	s_waitcnt lgkmcnt(0)
	v_cndmask_b32_e64 v92, v195, v187, s[14:15]
	v_exp_f32_e32 v89, v81
	v_pk_mul_f32 v[80:81], v[124:125], v[82:83]
	v_mul_f32_e32 v82, v94, v95
	v_fma_f32 v81, v106, v92, v81
	v_add_f32_e32 v80, v80, v81
	v_add_f32_e32 v80, v116, v80
	v_mul_f32_e32 v81, 0xbfb8aa3b, v80
	v_exp_f32_e32 v81, v81
	v_add_f32_e32 v83, 1.0, v89
	v_rcp_f32_e32 v83, v83
	v_mul_f32_e32 v82, v86, v82
	v_add_f32_e32 v81, 1.0, v81
	v_rcp_f32_e32 v81, v81
	v_mul_f32_e32 v83, v88, v83
	v_mul_f32_e32 v83, v85, v83
	v_mov_b32_e32 v98, 0
	v_mul_f32_e32 v80, v80, v81
	v_mul_f32_e32 v80, v84, v80
	v_cvt_pk_bf16_f32 v106, v80, v83
	v_or_b32_e32 v80, 48, v142
	v_mad_i64_i32 v[80:81], s[20:21], v80, s2, v[140:141]
	v_lshl_add_u64 v[80:81], v[80:81], 0, v[138:139]
	v_cvt_pk_bf16_f32 v107, v82, v87
	global_store_dwordx4 v[80:81], v[104:107], off
	ds_read_b128 v[94:97], v174
	ds_read_b128 v[90:93], v175
	ds_read_b128 v[82:85], v176
	ds_read_b128 v[86:89], v177
	v_cndmask_b32_e64 v80, 0, 1, s[52:53]
	v_cmp_ne_u32_e64 s[20:21], 1, v80
	s_andn2_b64 vcc, exec, s[52:53]
	v_mov_b32_e32 v102, 0
	v_mov_b32_e32 v103, 0
	v_mov_b32_e32 v104, 0
	v_mov_b32_e32 v105, 0
	s_cbranch_vccnz .LBB0_1009
	ds_read_b128 v[102:105], v172 offset:1536

.LBB0_1011:
	v_mov_b32_dpp v112, v75 row_ror:1 row_mask:0xf bank_mask:0xf
	v_mov_b32_dpp v113, v75 row_ror:15 row_mask:0xf bank_mask:0xf
	v_mov_b32_dpp v121, v71 row_ror:15 row_mask:0xf bank_mask:0xf
	v_mov_b32_dpp v108, v74 row_ror:1 row_mask:0xf bank_mask:0xf
	v_mov_b32_dpp v109, v74 row_ror:15 row_mask:0xf bank_mask:0xf
	s_waitcnt lgkmcnt(0)
	v_cndmask_b32_e64 v105, v112, v105, s[14:15]
	v_mul_f32_e32 v105, v97, v105
	s_waitcnt lgkmcnt(0)
	v_cndmask_b32_e64 v113, v113, v121, s[16:17]
	v_fmac_f32_e32 v105, v75, v93
	v_mov_b32_dpp v119, v70 row_ror:15 row_mask:0xf bank_mask:0xf
	v_fmac_f32_e32 v105, v85, v113
	v_add_f32_e32 v75, v89, v105
	v_mul_f32_e32 v105, 0xbfb8aa3b, v75
	v_mov_b32_dpp v106, v72 row_ror:1 row_mask:0xf bank_mask:0xf
	v_mov_b32_dpp v107, v73 row_ror:1 row_mask:0xf bank_mask:0xf
	v_exp_f32_e32 v105, v105
	s_waitcnt lgkmcnt(0)
	v_cndmask_b32_e64 v104, v108, v104, s[14:15]
	v_mul_f32_e32 v104, v96, v104
	v_mov_b32_dpp v80, v72 row_ror:15 row_mask:0xf bank_mask:0xf
	v_mov_b32_dpp v81, v73 row_ror:15 row_mask:0xf bank_mask:0xf
	v_mov_b32_dpp v115, v68 row_ror:15 row_mask:0xf bank_mask:0xf
	v_mov_b32_dpp v117, v69 row_ror:15 row_mask:0xf bank_mask:0xf
	s_waitcnt lgkmcnt(0)
	v_cndmask_b32_e64 v109, v109, v119, s[16:17]
	v_fmac_f32_e32 v104, v74, v92
	v_fmac_f32_e32 v104, v84, v109
	v_add_f32_e32 v105, 1.0, v105
	v_add_f32_e32 v74, v88, v104
	s_waitcnt lgkmcnt(0)
	v_cndmask_b32_e64 v102, v106, v102, s[14:15]
	s_waitcnt lgkmcnt(0)
	v_cndmask_b32_e64 v103, v107, v103, s[14:15]
	v_rcp_f32_e32 v105, v105
	v_mul_f32_e32 v104, 0xbfb8aa3b, v74
	v_exp_f32_e32 v104, v104
	v_mul_f32_e32 v103, v95, v103
	v_mul_f32_e32 v102, v94, v102
	s_waitcnt lgkmcnt(0)
	v_cndmask_b32_e64 v80, v80, v115, s[16:17]
	s_waitcnt lgkmcnt(0)
	v_cndmask_b32_e64 v81, v81, v117, s[16:17]
	v_fmac_f32_e32 v103, v73, v91
	v_fmac_f32_e32 v102, v72, v90
	v_fmac_f32_e32 v103, v83, v81
	v_fmac_f32_e32 v102, v82, v80
	v_mul_f32_e32 v75, v75, v105
	v_add_f32_e32 v73, v87, v103
	v_add_f32_e32 v72, v86, v102
	v_mul_f32_e32 v75, v79, v75
	v_add_f32_e32 v79, 1.0, v104
	v_mul_f32_e32 v81, 0xbfb8aa3b, v73
	v_mul_f32_e32 v80, 0xbfb8aa3b, v72
	v_rcp_f32_e32 v79, v79
	v_exp_f32_e32 v81, v81
	v_exp_f32_e32 v80, v80
	v_mov_b32_dpp v120, v71 row_ror:1 row_mask:0xf bank_mask:0xf
	v_mul_f32_e32 v74, v74, v79
	v_add_f32_e32 v79, 1.0, v81
	v_add_f32_e32 v80, 1.0, v80
	v_rcp_f32_e32 v79, v79
	v_rcp_f32_e32 v80, v80
	v_mov_b32_dpp v129, v63 row_ror:15 row_mask:0xf bank_mask:0xf
	v_mul_f32_e32 v74, v78, v74
	v_mul_f32_e32 v73, v73, v79
	v_mul_f32_e32 v72, v72, v80
	v_mul_f32_e32 v73, v77, v73
	v_mul_f32_e32 v72, v76, v72
	v_cvt_pk_bf16_f32 v80, v72, v73
	v_cvt_pk_bf16_f32 v81, v74, v75
	s_waitcnt lgkmcnt(0)
	v_cndmask_b32_e64 v74, v120, v112, s[14:15]
	v_mov_b32_dpp v118, v70 row_ror:1 row_mask:0xf bank_mask:0xf
	v_mul_f32_e32 v74, v97, v74
	s_waitcnt lgkmcnt(0)
	v_cndmask_b32_e64 v75, v121, v129, s[16:17]
	v_fmac_f32_e32 v74, v71, v93
	v_mov_b32_dpp v127, v62 row_ror:15 row_mask:0xf bank_mask:0xf
	v_fmac_f32_e32 v74, v85, v75
	v_add_f32_e32 v71, v89, v74
	v_mul_f32_e32 v74, 0xbfb8aa3b, v71
	v_mov_b32_dpp v114, v68 row_ror:1 row_mask:0xf bank_mask:0xf
	v_mov_b32_dpp v116, v69 row_ror:1 row_mask:0xf bank_mask:0xf
	v_exp_f32_e32 v74, v74
	s_waitcnt lgkmcnt(0)
	v_cndmask_b32_e64 v75, v118, v108, s[14:15]
	v_mul_f32_e32 v75, v96, v75
	v_mov_b32_dpp v123, v60 row_ror:15 row_mask:0xf bank_mask:0xf
	v_mov_b32_dpp v125, v61 row_ror:15 row_mask:0xf bank_mask:0xf
	s_waitcnt lgkmcnt(0)
	v_cndmask_b32_e64 v77, v119, v127, s[16:17]
	v_fmac_f32_e32 v75, v70, v92
	v_fmac_f32_e32 v75, v84, v77
	v_add_f32_e32 v74, 1.0, v74
	v_add_f32_e32 v70, v88, v75
	s_waitcnt lgkmcnt(0)
	v_cndmask_b32_e64 v72, v114, v106, s[14:15]
	s_waitcnt lgkmcnt(0)
	v_cndmask_b32_e64 v73, v116, v107, s[14:15]
	v_rcp_f32_e32 v74, v74
	v_mul_f32_e32 v75, 0xbfb8aa3b, v70
	v_exp_f32_e32 v75, v75
	v_mul_f32_e32 v73, v95, v73
	v_mul_f32_e32 v72, v94, v72
	s_waitcnt lgkmcnt(0)
	v_cndmask_b32_e64 v76, v115, v123, s[16:17]
	s_waitcnt lgkmcnt(0)
	v_cndmask_b32_e64 v77, v117, v125, s[16:17]
	v_fmac_f32_e32 v73, v69, v91
	v_fmac_f32_e32 v72, v68, v90
	v_fmac_f32_e32 v73, v83, v77
	v_fmac_f32_e32 v72, v82, v76
	v_mul_f32_e32 v71, v71, v74
	v_add_f32_e32 v69, v87, v73
	v_add_f32_e32 v68, v86, v72
	v_mul_f32_e32 v67, v67, v71
	v_add_f32_e32 v71, 1.0, v75
	v_mul_f32_e32 v73, 0xbfb8aa3b, v69
	v_mul_f32_e32 v72, 0xbfb8aa3b, v68
	v_rcp_f32_e32 v71, v71
	v_exp_f32_e32 v73, v73
	v_exp_f32_e32 v72, v72
	v_mov_b32_dpp v128, v63 row_ror:1 row_mask:0xf bank_mask:0xf
	v_mul_f32_e32 v70, v70, v71
	v_add_f32_e32 v71, 1.0, v73
	v_add_f32_e32 v72, 1.0, v72
	v_rcp_f32_e32 v71, v71
	v_rcp_f32_e32 v72, v72
	v_mov_b32_dpp v137, v19 row_ror:15 row_mask:0xf bank_mask:0xf
	v_mul_f32_e32 v66, v66, v70
	v_mul_f32_e32 v69, v69, v71
	v_mul_f32_e32 v68, v68, v72
	v_mul_f32_e32 v65, v65, v69
	v_mul_f32_e32 v64, v64, v68
	v_cvt_pk_bf16_f32 v78, v64, v65
	v_cvt_pk_bf16_f32 v79, v66, v67
	s_waitcnt lgkmcnt(0)
	v_cndmask_b32_e64 v66, v128, v120, s[14:15]
	v_mov_b32_dpp v126, v62 row_ror:1 row_mask:0xf bank_mask:0xf
	v_mul_f32_e32 v66, v97, v66
	s_waitcnt lgkmcnt(0)
	v_cndmask_b32_e64 v67, v129, v137, s[16:17]
	v_fmac_f32_e32 v66, v63, v93
	v_mov_b32_dpp v135, v18 row_ror:15 row_mask:0xf bank_mask:0xf
	v_fmac_f32_e32 v66, v85, v67
	v_add_f32_e32 v63, v89, v66
	v_mul_f32_e32 v66, 0xbfb8aa3b, v63
	v_mov_b32_dpp v124, v61 row_ror:1 row_mask:0xf bank_mask:0xf
	v_exp_f32_e32 v66, v66
	s_waitcnt lgkmcnt(0)
	v_cndmask_b32_e64 v67, v126, v118, s[14:15]
	v_mov_b32_dpp v122, v60 row_ror:1 row_mask:0xf bank_mask:0xf
	v_mul_f32_e32 v67, v96, v67
	v_mov_b32_dpp v133, v17 row_ror:15 row_mask:0xf bank_mask:0xf
	s_waitcnt lgkmcnt(0)
	v_cndmask_b32_e64 v69, v127, v135, s[16:17]
	v_fmac_f32_e32 v67, v62, v92
	v_mov_b32_dpp v131, v16 row_ror:15 row_mask:0xf bank_mask:0xf
	v_fmac_f32_e32 v67, v84, v69
	v_add_f32_e32 v66, 1.0, v66
	v_add_f32_e32 v62, v88, v67
	s_waitcnt lgkmcnt(0)
	v_cndmask_b32_e64 v65, v124, v116, s[14:15]
	v_rcp_f32_e32 v66, v66
	v_mul_f32_e32 v67, 0xbfb8aa3b, v62
	s_waitcnt lgkmcnt(0)
	v_cndmask_b32_e64 v64, v122, v114, s[14:15]
	v_exp_f32_e32 v67, v67
	v_mul_f32_e32 v65, v95, v65
	s_waitcnt lgkmcnt(0)
	v_cndmask_b32_e64 v69, v125, v133, s[16:17]
	v_fmac_f32_e32 v65, v61, v91
	v_mul_f32_e32 v64, v94, v64
	s_waitcnt lgkmcnt(0)
	v_cndmask_b32_e64 v68, v123, v131, s[16:17]
	v_fmac_f32_e32 v65, v83, v69
	v_fmac_f32_e32 v64, v60, v90
	v_mul_f32_e32 v63, v63, v66
	v_add_f32_e32 v61, v87, v65
	v_fmac_f32_e32 v64, v82, v68
	v_mul_f32_e32 v59, v59, v63
	v_add_f32_e32 v63, 1.0, v67
	v_mul_f32_e32 v65, 0xbfb8aa3b, v61
	v_add_f32_e32 v60, v86, v64
	v_rcp_f32_e32 v63, v63
	v_exp_f32_e32 v65, v65
	v_mul_f32_e32 v64, 0xbfb8aa3b, v60
	v_exp_f32_e32 v64, v64
	v_mul_f32_e32 v62, v62, v63
	v_add_f32_e32 v63, 1.0, v65
	v_mov_b32_dpp v136, v19 row_ror:1 row_mask:0xf bank_mask:0xf
	v_rcp_f32_e32 v63, v63
	v_add_f32_e32 v64, 1.0, v64
	v_rcp_f32_e32 v64, v64
	v_mul_f32_e32 v62, v58, v62
	v_mul_f32_e32 v58, v61, v63
	v_mov_b32_dpp v134, v18 row_ror:1 row_mask:0xf bank_mask:0xf
	v_mul_f32_e32 v57, v57, v58
	v_mul_f32_e32 v58, v60, v64
	s_waitcnt lgkmcnt(0)
	v_cndmask_b32_e64 v60, v136, v128, s[14:15]
	v_mul_f32_e32 v60, v97, v60
	v_cndmask_b32_e64 v61, v137, v101, s[16:17]
	v_fmac_f32_e32 v60, v19, v93
	v_fmac_f32_e32 v60, v85, v61
	v_add_f32_e32 v60, v89, v60
	v_mov_b32_dpp v130, v16 row_ror:1 row_mask:0xf bank_mask:0xf
	v_mov_b32_dpp v132, v17 row_ror:1 row_mask:0xf bank_mask:0xf
	v_mul_f32_e32 v56, v56, v58
	v_cvt_pk_bf16_f32 v58, v56, v57
	v_cvt_pk_bf16_f32 v59, v62, v59
	v_mul_f32_e32 v61, 0xbfb8aa3b, v60
	s_waitcnt lgkmcnt(0)
	v_cndmask_b32_e64 v62, v134, v126, s[14:15]
	v_exp_f32_e32 v61, v61
	v_mul_f32_e32 v62, v96, v62
	v_cndmask_b32_e64 v64, v135, v100, s[16:17]
	v_fmac_f32_e32 v62, v18, v92
	v_fmac_f32_e32 v62, v84, v64
	v_add_f32_e32 v62, v88, v62
	s_waitcnt lgkmcnt(0)
	v_cndmask_b32_e64 v56, v130, v122, s[14:15]
	s_waitcnt lgkmcnt(0)
	v_cndmask_b32_e64 v57, v132, v124, s[14:15]
	v_add_f32_e32 v61, 1.0, v61
	v_mul_f32_e32 v64, 0xbfb8aa3b, v62
	v_rcp_f32_e32 v61, v61
	v_exp_f32_e32 v64, v64
	v_mul_f32_e32 v57, v95, v57
	v_mul_f32_e32 v56, v94, v56
	v_cndmask_b32_e64 v63, v131, v98, s[16:17]
	v_cndmask_b32_e64 v65, v133, v99, s[16:17]
	v_fmac_f32_e32 v57, v17, v91
	v_fmac_f32_e32 v56, v16, v90
	v_fmac_f32_e32 v57, v83, v65
	v_fmac_f32_e32 v56, v82, v63
	v_add_f32_e32 v57, v87, v57
	v_add_f32_e32 v56, v86, v56
	v_mul_f32_e32 v60, v60, v61
	v_add_f32_e32 v61, 1.0, v64
	v_mul_f32_e32 v64, 0xbfb8aa3b, v57
	v_mul_f32_e32 v63, 0xbfb8aa3b, v56
	v_rcp_f32_e32 v61, v61
	v_exp_f32_e32 v64, v64
	v_exp_f32_e32 v63, v63
	v_mul_f32_e32 v60, v11, v60
	v_mul_f32_e32 v61, v62, v61
	v_add_f32_e32 v62, 1.0, v64
	v_add_f32_e32 v63, 1.0, v63
	v_rcp_f32_e32 v62, v62
	v_rcp_f32_e32 v63, v63
	v_mul_f32_e32 v61, v10, v61
	v_mov_b32_e32 v84, 0
	v_mul_f32_e32 v57, v57, v62
	v_mul_f32_e32 v56, v56, v63
	v_mul_f32_e32 v57, v9, v57
	v_mul_f32_e32 v56, v8, v56
	v_cvt_pk_bf16_f32 v56, v56, v57
	v_cvt_pk_bf16_f32 v57, v61, v60
	ds_read_b128 v[62:65], v174 offset:16
	ds_read_b128 v[70:73], v174 offset:528
	ds_read_b128 v[74:77], v174 offset:1040
	ds_read_b128 v[66:69], v174 offset:1552
	s_and_b64 vcc, exec, s[20:21]
	v_mov_b32_e32 v88, 0
	v_mov_b32_e32 v89, 0
	v_mov_b32_e32 v90, 0
	v_mov_b32_e32 v91, 0
	s_cbranch_vccnz .LBB0_1013
	ds_read_b128 v[88:91], v172 offset:1552

.LBB0_1015:
	v_mov_b32_dpp v60, v51 row_ror:15 row_mask:0xf bank_mask:0xf
	v_mov_b32_dpp v107, v47 row_ror:15 row_mask:0xf bank_mask:0xf
	v_mov_b32_dpp v99, v51 row_ror:1 row_mask:0xf bank_mask:0xf
	v_mov_b32_e32 v82, v51
	s_waitcnt lgkmcnt(0)
	v_mov_b32_e32 v83, v77
	v_mov_b32_dpp v98, v50 row_ror:15 row_mask:0xf bank_mask:0xf
	s_waitcnt lgkmcnt(0)
	v_cndmask_b32_e64 v61, v60, v107, s[16:17]
	v_mov_b32_e32 v60, v73
	s_waitcnt lgkmcnt(0)
	v_cndmask_b32_e64 v91, v99, v91, s[14:15]
	v_pk_mul_f32 v[60:61], v[82:83], v[60:61]
	v_mov_b32_dpp v105, v46 row_ror:15 row_mask:0xf bank_mask:0xf
	v_fma_f32 v51, v65, v91, v60
	v_add_f32_e32 v51, v51, v61
	v_add_f32_e32 v60, v69, v51
	v_mul_f32_e32 v51, 0xbfb8aa3b, v60
	v_exp_f32_e32 v51, v51
	v_mov_b32_dpp v97, v50 row_ror:1 row_mask:0xf bank_mask:0xf
	v_mov_b32_dpp v96, v49 row_ror:15 row_mask:0xf bank_mask:0xf
	v_mov_b32_dpp v103, v45 row_ror:15 row_mask:0xf bank_mask:0xf
	v_add_f32_e32 v51, 1.0, v51
	s_waitcnt lgkmcnt(0)
	v_cndmask_b32_e64 v83, v98, v105, s[16:17]
	v_rcp_f32_e32 v91, v51
	v_mov_b32_e32 v51, v76
	v_mov_b32_e32 v82, v72
	v_mov_b32_dpp v95, v49 row_ror:1 row_mask:0xf bank_mask:0xf
	s_waitcnt lgkmcnt(0)
	v_cndmask_b32_e64 v90, v97, v90, s[14:15]
	v_pk_mul_f32 v[50:51], v[50:51], v[82:83]
	v_mul_f32_e32 v60, v60, v91
	v_fma_f32 v50, v64, v90, v50
	v_add_f32_e32 v50, v50, v51
	v_add_f32_e32 v90, v68, v50
	s_waitcnt lgkmcnt(0)
	v_cndmask_b32_e64 v61, v96, v103, s[16:17]
	v_mul_f32_e32 v50, 0xbfb8aa3b, v90
	v_mul_f32_e32 v55, v55, v60
	v_mov_b32_e32 v82, v49
	v_mov_b32_e32 v83, v75
	v_mov_b32_e32 v60, v71
	v_mov_b32_dpp v94, v48 row_ror:15 row_mask:0xf bank_mask:0xf
	v_mov_b32_dpp v101, v44 row_ror:15 row_mask:0xf bank_mask:0xf
	s_waitcnt lgkmcnt(0)
	v_cndmask_b32_e64 v89, v95, v89, s[14:15]
	v_exp_f32_e32 v50, v50
	v_pk_mul_f32 v[60:61], v[82:83], v[60:61]
	v_mov_b32_dpp v93, v48 row_ror:1 row_mask:0xf bank_mask:0xf
	v_fma_f32 v49, v63, v89, v60
	v_add_f32_e32 v49, v49, v61
	v_add_f32_e32 v60, v67, v49
	v_add_f32_e32 v50, 1.0, v50
	v_mul_f32_e32 v49, 0xbfb8aa3b, v60
	s_waitcnt lgkmcnt(0)
	v_cndmask_b32_e64 v51, v94, v101, s[16:17]
	v_rcp_f32_e32 v91, v50
	v_exp_f32_e32 v61, v49
	v_mov_b32_e32 v49, v74
	v_mov_b32_e32 v50, v70
	s_waitcnt lgkmcnt(0)
	v_cndmask_b32_e64 v88, v93, v88, s[14:15]
	v_pk_mul_f32 v[48:49], v[48:49], v[50:51]
	v_add_f32_e32 v51, 1.0, v61
	v_fma_f32 v48, v62, v88, v48
	v_add_f32_e32 v48, v48, v49
	v_add_f32_e32 v48, v66, v48
	v_mul_f32_e32 v49, 0xbfb8aa3b, v48
	v_exp_f32_e32 v49, v49
	v_rcp_f32_e32 v51, v51
	v_mov_b32_dpp v117, v39 row_ror:15 row_mask:0xf bank_mask:0xf
	v_mov_b32_dpp v106, v47 row_ror:1 row_mask:0xf bank_mask:0xf
	v_add_f32_e32 v49, 1.0, v49
	v_rcp_f32_e32 v49, v49
	v_mul_f32_e32 v50, v90, v91
	v_mul_f32_e32 v51, v60, v51
	v_add_u32_e32 v92, 0x80, v142
	v_mul_f32_e32 v48, v48, v49
	v_mul_f32_e32 v48, v52, v48
	v_mul_f32_e32 v50, v54, v50
	v_mul_f32_e32 v51, v53, v51
	v_cvt_pk_bf16_f32 v82, v48, v51
	v_mov_b64_e32 v[48:49], s[28:29]
	v_cvt_pk_bf16_f32 v83, v50, v55
	v_mad_i64_i32 v[50:51], s[20:21], v92, s2, v[48:49]
	v_lshl_add_u64 v[50:51], v[50:51], 0, v[138:139]
	global_store_dwordx4 v[50:51], v[80:83], off
	s_waitcnt lgkmcnt(0)
	v_cndmask_b32_e64 v50, v107, v117, s[16:17]
	v_mov_b32_e32 v52, v77
	v_mov_b32_e32 v53, v47
	v_mov_b32_e32 v51, v73
	s_waitcnt lgkmcnt(0)
	v_cndmask_b32_e64 v54, v106, v99, s[14:15]
	v_pk_mul_f32 v[50:51], v[52:53], v[50:51]
	v_mov_b32_dpp v115, v38 row_ror:15 row_mask:0xf bank_mask:0xf
	v_fma_f32 v47, v65, v54, v51
	v_add_f32_e32 v47, v50, v47
	v_add_f32_e32 v51, v69, v47
	v_mul_f32_e32 v47, 0xbfb8aa3b, v51
	v_mov_b32_dpp v104, v46 row_ror:1 row_mask:0xf bank_mask:0xf
	v_exp_f32_e32 v47, v47
	s_waitcnt lgkmcnt(0)
	v_cndmask_b32_e64 v52, v105, v115, s[16:17]
	v_mov_b32_e32 v54, v76
	v_mov_b32_e32 v55, v46
	v_add_f32_e32 v47, 1.0, v47
	v_mov_b32_e32 v53, v72
	s_waitcnt lgkmcnt(0)
	v_cndmask_b32_e64 v80, v104, v97, s[14:15]
	v_rcp_f32_e32 v81, v47
	v_pk_mul_f32 v[46:47], v[54:55], v[52:53]
	v_mov_b32_dpp v113, v37 row_ror:15 row_mask:0xf bank_mask:0xf
	v_fma_f32 v47, v64, v80, v47
	v_add_f32_e32 v46, v46, v47
	v_add_f32_e32 v54, v68, v46
	v_mul_f32_e32 v46, 0xbfb8aa3b, v54
	v_exp_f32_e32 v47, v46
	v_mov_b32_dpp v102, v45 row_ror:1 row_mask:0xf bank_mask:0xf
	v_mov_b32_dpp v109, v36 row_ror:15 row_mask:0xf bank_mask:0xf
	s_waitcnt lgkmcnt(0)
	v_cndmask_b32_e64 v46, v103, v113, s[16:17]
	v_add_f32_e32 v47, 1.0, v47
	v_rcp_f32_e32 v55, v47
	v_mov_b32_e32 v52, v75
	v_mov_b32_e32 v53, v45
	v_mov_b32_e32 v47, v71
	v_mov_b32_dpp v100, v44 row_ror:1 row_mask:0xf bank_mask:0xf
	s_waitcnt lgkmcnt(0)
	v_cndmask_b32_e64 v61, v102, v95, s[14:15]
	v_pk_mul_f32 v[46:47], v[52:53], v[46:47]
	v_mul_f32_e32 v51, v51, v81
	v_fma_f32 v45, v63, v61, v47
	v_add_f32_e32 v45, v46, v45
	v_add_f32_e32 v52, v67, v45
	s_waitcnt lgkmcnt(0)
	v_cndmask_b32_e64 v50, v101, v109, s[16:17]
	v_mul_f32_e32 v43, v43, v51
	v_mul_f32_e32 v45, 0xbfb8aa3b, v52
	v_mov_b32_e32 v46, v74
	v_mov_b32_e32 v47, v44
	v_mov_b32_e32 v51, v70
	s_waitcnt lgkmcnt(0)
	v_cndmask_b32_e64 v60, v100, v93, s[14:15]
	v_exp_f32_e32 v53, v45
	v_pk_mul_f32 v[44:45], v[46:47], v[50:51]
	v_mov_b32_dpp v125, v3 row_ror:15 row_mask:0xf bank_mask:0xf
	v_fma_f32 v45, v62, v60, v45
	v_add_f32_e32 v44, v44, v45
	v_add_f32_e32 v44, v66, v44
	v_mul_f32_e32 v45, 0xbfb8aa3b, v44
	v_exp_f32_e32 v45, v45
	v_add_f32_e32 v47, 1.0, v53
	v_rcp_f32_e32 v47, v47
	v_mul_f32_e32 v46, v54, v55
	v_add_f32_e32 v45, 1.0, v45
	v_rcp_f32_e32 v45, v45
	v_mov_b32_dpp v116, v39 row_ror:1 row_mask:0xf bank_mask:0xf
	v_mul_f32_e32 v42, v42, v46
	v_mul_f32_e32 v46, v52, v47
	v_mul_f32_e32 v44, v44, v45
	v_mul_f32_e32 v40, v40, v44
	v_mul_f32_e32 v41, v41, v46
	v_cvt_pk_bf16_f32 v80, v40, v41
	v_add_u32_e32 v40, 0x90, v142
	v_mad_i64_i32 v[40:41], s[20:21], v40, s2, v[48:49]
	v_lshl_add_u64 v[40:41], v[40:41], 0, v[138:139]
	v_cvt_pk_bf16_f32 v81, v42, v43
	global_store_dwordx4 v[40:41], v[78:81], off
	s_waitcnt lgkmcnt(0)
	v_cndmask_b32_e64 v40, v117, v125, s[16:17]
	v_mov_b32_e32 v42, v77
	v_mov_b32_e32 v43, v39
	v_mov_b32_e32 v41, v73
	s_waitcnt lgkmcnt(0)
	v_cndmask_b32_e64 v44, v116, v106, s[14:15]
	v_pk_mul_f32 v[40:41], v[42:43], v[40:41]
	v_mov_b32_dpp v123, v2 row_ror:15 row_mask:0xf bank_mask:0xf
	v_fma_f32 v39, v65, v44, v41
	v_add_f32_e32 v39, v40, v39
	v_add_f32_e32 v41, v69, v39
	v_mul_f32_e32 v39, 0xbfb8aa3b, v41
	v_mov_b32_dpp v114, v38 row_ror:1 row_mask:0xf bank_mask:0xf
	v_exp_f32_e32 v39, v39
	s_waitcnt lgkmcnt(0)
	v_cndmask_b32_e64 v42, v115, v123, s[16:17]
	v_mov_b32_e32 v44, v76
	v_mov_b32_e32 v45, v38
	v_add_f32_e32 v39, 1.0, v39
	v_mov_b32_e32 v43, v72
	s_waitcnt lgkmcnt(0)
	v_cndmask_b32_e64 v50, v114, v104, s[14:15]
	v_rcp_f32_e32 v51, v39
	v_pk_mul_f32 v[38:39], v[44:45], v[42:43]
	v_mov_b32_dpp v121, v1 row_ror:15 row_mask:0xf bank_mask:0xf
	v_fma_f32 v39, v64, v50, v39
	v_add_f32_e32 v38, v38, v39
	v_add_f32_e32 v44, v68, v38
	v_mul_f32_e32 v38, 0xbfb8aa3b, v44
	v_exp_f32_e32 v39, v38
	v_mov_b32_dpp v112, v37 row_ror:1 row_mask:0xf bank_mask:0xf
	v_mov_b32_dpp v119, v0 row_ror:15 row_mask:0xf bank_mask:0xf
	s_waitcnt lgkmcnt(0)
	v_cndmask_b32_e64 v38, v113, v121, s[16:17]
	v_add_f32_e32 v39, 1.0, v39
	v_rcp_f32_e32 v45, v39
	v_mov_b32_e32 v42, v75
	v_mov_b32_e32 v43, v37
	v_mov_b32_e32 v39, v71
	v_mov_b32_dpp v108, v36 row_ror:1 row_mask:0xf bank_mask:0xf
	s_waitcnt lgkmcnt(0)
	v_cndmask_b32_e64 v47, v112, v102, s[14:15]
	v_pk_mul_f32 v[38:39], v[42:43], v[38:39]
	v_mul_f32_e32 v41, v41, v51
	v_fma_f32 v37, v63, v47, v39
	v_add_f32_e32 v37, v38, v37
	v_add_f32_e32 v42, v67, v37
	s_waitcnt lgkmcnt(0)
	v_cndmask_b32_e64 v40, v109, v119, s[16:17]
	v_mul_f32_e32 v35, v35, v41
	v_mul_f32_e32 v37, 0xbfb8aa3b, v42
	v_mov_b32_e32 v38, v74
	v_mov_b32_e32 v39, v36
	v_mov_b32_e32 v41, v70
	s_waitcnt lgkmcnt(0)
	v_cndmask_b32_e64 v46, v108, v100, s[14:15]
	v_exp_f32_e32 v43, v37
	v_pk_mul_f32 v[36:37], v[38:39], v[40:41]
	v_mul_f32_e32 v38, v44, v45
	v_fma_f32 v37, v62, v46, v37
	v_add_f32_e32 v36, v36, v37
	v_add_f32_e32 v36, v66, v36
	v_mul_f32_e32 v37, 0xbfb8aa3b, v36
	v_exp_f32_e32 v37, v37
	v_add_f32_e32 v39, 1.0, v43
	v_rcp_f32_e32 v39, v39
	v_mov_b32_dpp v124, v3 row_ror:1 row_mask:0xf bank_mask:0xf
	v_add_f32_e32 v37, 1.0, v37
	v_rcp_f32_e32 v37, v37
	v_mul_f32_e32 v34, v34, v38
	v_mul_f32_e32 v38, v42, v39
	v_mul_f32_e32 v33, v33, v38
	v_mul_f32_e32 v36, v36, v37
	v_mul_f32_e32 v32, v32, v36
	v_cvt_pk_bf16_f32 v60, v32, v33
	v_add_u32_e32 v32, 0xa0, v142
	v_mad_i64_i32 v[32:33], s[20:21], v32, s2, v[48:49]
	v_lshl_add_u64 v[32:33], v[32:33], 0, v[138:139]
	v_cvt_pk_bf16_f32 v61, v34, v35
	global_store_dwordx4 v[32:33], v[58:61], off
	v_cndmask_b32_e64 v32, v125, v87, s[16:17]
	v_mov_b32_e32 v34, v77
	v_mov_b32_e32 v35, v3
	v_mov_b32_e32 v33, v73
	s_waitcnt lgkmcnt(0)
	v_cndmask_b32_e64 v36, v124, v116, s[14:15]
	v_pk_mul_f32 v[32:33], v[34:35], v[32:33]
	v_mov_b32_dpp v122, v2 row_ror:1 row_mask:0xf bank_mask:0xf
	v_fma_f32 v33, v65, v36, v33
	v_add_f32_e32 v32, v32, v33
	v_add_f32_e32 v33, v69, v32
	v_mul_f32_e32 v32, 0xbfb8aa3b, v33
	v_exp_f32_e32 v35, v32
	v_cndmask_b32_e64 v34, v123, v86, s[16:17]
	v_mov_b32_e32 v77, v2
	s_waitcnt lgkmcnt(0)
	v_cndmask_b32_e64 v36, v122, v114, s[14:15]
	v_add_f32_e32 v35, 1.0, v35
	v_rcp_f32_e32 v37, v35
	v_mov_b32_e32 v35, v72
	v_pk_mul_f32 v[34:35], v[76:77], v[34:35]
	v_mov_b32_dpp v120, v1 row_ror:1 row_mask:0xf bank_mask:0xf
	v_fma_f32 v35, v64, v36, v35
	v_add_f32_e32 v34, v34, v35
	v_add_f32_e32 v40, v68, v34
	v_mul_f32_e32 v34, 0xbfb8aa3b, v40
	v_exp_f32_e32 v35, v34
	v_mul_f32_e32 v33, v33, v37
	v_mul_f32_e32 v41, v7, v33
	v_cndmask_b32_e64 v32, v121, v85, s[16:17]
	v_add_f32_e32 v33, 1.0, v35
	v_rcp_f32_e32 v42, v33
	v_mov_b32_e32 v36, v75
	v_mov_b32_e32 v37, v1
	v_mov_b32_e32 v33, v71
	v_mov_b32_dpp v118, v0 row_ror:1 row_mask:0xf bank_mask:0xf
	s_waitcnt lgkmcnt(0)
	v_cndmask_b32_e64 v39, v120, v112, s[14:15]
	v_pk_mul_f32 v[32:33], v[36:37], v[32:33]
	v_cndmask_b32_e64 v34, v119, v84, s[16:17]
	v_fma_f32 v33, v63, v39, v33
	v_add_f32_e32 v32, v32, v33
	v_add_f32_e32 v36, v67, v32
	v_mul_f32_e32 v32, 0xbfb8aa3b, v36
	v_mov_b32_e32 v75, v0
	v_mov_b32_e32 v35, v70
	s_waitcnt lgkmcnt(0)
	v_cndmask_b32_e64 v38, v118, v108, s[14:15]
	v_exp_f32_e32 v37, v32
	v_pk_mul_f32 v[32:33], v[74:75], v[34:35]
	v_mul_f32_e32 v34, v40, v42
	v_fma_f32 v33, v62, v38, v33
	v_add_f32_e32 v32, v32, v33
	v_add_f32_e32 v32, v66, v32
	v_mul_f32_e32 v33, 0xbfb8aa3b, v32
	v_exp_f32_e32 v33, v33
	v_add_f32_e32 v35, 1.0, v37
	v_rcp_f32_e32 v35, v35
	v_mul_f32_e32 v34, v6, v34
	v_add_f32_e32 v33, 1.0, v33
	v_rcp_f32_e32 v33, v33
	v_mul_f32_e32 v35, v36, v35
	v_mul_f32_e32 v35, v5, v35
	v_mul_f32_e32 v32, v32, v33
	v_mul_f32_e32 v32, v4, v32
	v_cvt_pk_bf16_f32 v58, v32, v35
	v_add_u32_e32 v32, 0xb0, v142
	v_mad_i64_i32 v[32:33], s[20:21], v32, s2, v[48:49]
	v_lshl_add_u64 v[32:33], v[32:33], 0, v[138:139]
	v_cvt_pk_bf16_f32 v59, v34, v41
	global_store_dwordx4 v[32:33], v[56:59], off
	s_and_saveexec_b64 s[20:21], s[4:5]
	s_cbranch_execnz .LBB0_1018
	s_or_b64 exec, exec, s[20:21]
	s_and_saveexec_b64 s[20:21], s[26:27]
	s_cbranch_execnz .LBB0_1021
